# grid barrier: non-leader workgroups wait on the top-level generation word directly (one relay hop less)
# speedup vs baseline: 1.0066x; 1.0066x over previous
; __device__ __forceinline__ unsigned xb_ld(unsigned* p)              { return __hip_atomic_load(p, __ATOMIC_RELAXED, __HIP_MEMORY_SCOPE_AGENT); }
; __device__ __forceinline__ unsigned xb_add(unsigned* p, unsigned v) { return __hip_atomic_fetch_add(p, v, __ATOMIC_RELAXED, __HIP_MEMORY_SCOPE_AGENT); }
; #define XB_SPIN(cond, bar) do { unsigned _sp = 0; while (cond) { __builtin_amdgcn_s_sleep(1); \
;     if ((++_sp & 255u) == 0u) { if (xb_ld(&(bar)[XB_TMO])) break; if (_sp > XB_SPIN_CAP) { atomicAdd(&(bar)[XB_TMO], 1u); break; } } } } while (0)
; __device__ __forceinline__ void grid_barrier(unsigned* bar, unsigned G, int tid, volatile LAS unsigned* st) {
;     ...
;         const unsigned old = xb_add(&bar[XB_XSUB(x)], 1u);
;         const unsigned gen = old / nloc;
;         if (old + 1u == (gen + 1u) * nloc) {
;             __builtin_amdgcn_fence(__ATOMIC_RELEASE, "agent");
;             asm volatile("s_waitcnt vmcnt(0)" ::: "memory");
;             const unsigned og = xb_add(&bar[XB_TOP], 1u);
;             const unsigned tg = og / nx;
;             if (og + 1u == (tg + 1u) * nx) xb_add(&bar[XB_TOPGEN], 1u);
;             else XB_SPIN(xb_ld(&bar[XB_TOPGEN]) == tg, bar);
;             __builtin_amdgcn_fence(__ATOMIC_ACQUIRE, "agent");
;             xb_add(&bar[XB_XGEN(x)], 1u);
;             asm volatile("s_waitcnt vmcnt(0)" ::: "memory");
;         } else {
;             XB_SPIN(xb_ld(&bar[XB_XGEN(x)]) == gen, bar);
;             __builtin_amdgcn_fence(__ATOMIC_ACQUIRE, "agent");
;             asm volatile("s_waitcnt vmcnt(0)" ::: "memory");
;         }
.LBB0_135:
	s_or_b64 exec, exec, s[8:9]
	v_cvt_f32_u32_e32 v4, v2
	s_waitcnt vmcnt(0)
	v_readfirstlane_b32 s4, v3
	v_sub_u32_e32 v3, 0, v2
	v_rcp_iflag_f32_e32 v4, v4
	v_add_u32_e32 v5, s4, v1
	v_mul_f32_e32 v4, 0x4f7ffffe, v4
	v_cvt_u32_f32_e32 v4, v4
	v_mul_lo_u32 v1, v3, v4
	v_mul_hi_u32 v1, v4, v1
	v_add_u32_e32 v1, v4, v1
	v_mul_hi_u32 v1, v5, v1
	v_mul_lo_u32 v3, v1, v2
	v_sub_u32_e32 v3, v5, v3
	v_add_u32_e32 v4, 1, v1
	v_cmp_ge_u32_e32 vcc, v3, v2
	s_nop 1
	v_cndmask_b32_e32 v1, v1, v4, vcc
	v_sub_u32_e32 v4, v3, v2
	v_cndmask_b32_e32 v3, v3, v4, vcc
	v_add_u32_e32 v4, 1, v1
	v_cmp_ge_u32_e32 vcc, v3, v2
	v_add_u32_e32 v3, 1, v5
	s_nop 0
	v_cndmask_b32_e32 v1, v1, v4, vcc
	v_mul_lo_u32 v4, v2, v1
	v_add_u32_e32 v2, v4, v2
	v_cmp_ne_u32_e32 vcc, v3, v2
	s_and_saveexec_b64 s[4:5], vcc
	s_xor_b64 s[4:5], exec, s[4:5]
	s_cbranch_execz .LBB0_149
	s_waitcnt lgkmcnt(0)
	v_mov_b32_e32 v0, 0x2000
	s_getreg_b32 s10, hwreg(HW_REG_XCC_ID, 0, 4)
	s_lshl_b32 s10, s10, 8
	s_sub_u32 s10, s2, s10
	s_subb_u32 s11, s3, 0
	s_add_u32 s10, s10, 0x3500
	s_addc_u32 s11, s11, 0
	v_mov_b32_e32 v0, 0
	global_load_dword v0, v0, s[10:11] sc1
	s_waitcnt vmcnt(0)
	v_cmp_eq_u32_e32 vcc, v0, v1
	s_and_saveexec_b64 s[8:9], vcc
	s_cbranch_execz .LBB0_148
	s_mov_b32 s22, 1
	s_mov_b64 s[12:13], 0
	v_mov_b32_e32 v0, 0
	s_branch .LBB0_139

; __device__ __forceinline__ unsigned xb_ld(unsigned* p)              { return __hip_atomic_load(p, __ATOMIC_RELAXED, __HIP_MEMORY_SCOPE_AGENT); }
; __device__ __forceinline__ unsigned xb_add(unsigned* p, unsigned v) { return __hip_atomic_fetch_add(p, v, __ATOMIC_RELAXED, __HIP_MEMORY_SCOPE_AGENT); }
; #define XB_SPIN(cond, bar) do { unsigned _sp = 0; while (cond) { __builtin_amdgcn_s_sleep(1); \
;     if ((++_sp & 255u) == 0u) { if (xb_ld(&(bar)[XB_TMO])) break; if (_sp > XB_SPIN_CAP) { atomicAdd(&(bar)[XB_TMO], 1u); break; } } } } while (0)
; __device__ __forceinline__ void grid_barrier(unsigned* bar, unsigned G, int tid, volatile LAS unsigned* st) {
;     ...
;         const unsigned old = xb_add(&bar[XB_XSUB(x)], 1u);
;         const unsigned gen = old / nloc;
;         if (old + 1u == (gen + 1u) * nloc) {
;             __builtin_amdgcn_fence(__ATOMIC_RELEASE, "agent");
;             asm volatile("s_waitcnt vmcnt(0)" ::: "memory");
;             const unsigned og = xb_add(&bar[XB_TOP], 1u);
;             const unsigned tg = og / nx;
;             if (og + 1u == (tg + 1u) * nx) xb_add(&bar[XB_TOPGEN], 1u);
;             else XB_SPIN(xb_ld(&bar[XB_TOPGEN]) == tg, bar);
;             __builtin_amdgcn_fence(__ATOMIC_ACQUIRE, "agent");
;             xb_add(&bar[XB_XGEN(x)], 1u);
;             asm volatile("s_waitcnt vmcnt(0)" ::: "memory");
;         } else {
;             XB_SPIN(xb_ld(&bar[XB_XGEN(x)]) == gen, bar);
;             __builtin_amdgcn_fence(__ATOMIC_ACQUIRE, "agent");
;             asm volatile("s_waitcnt vmcnt(0)" ::: "memory");
;         }
.LBB0_348:
	s_or_b64 exec, exec, s[8:9]
	v_cvt_f32_u32_e32 v4, v2
	s_waitcnt vmcnt(0)
	v_readfirstlane_b32 s6, v3
	v_sub_u32_e32 v3, 0, v2
	v_rcp_iflag_f32_e32 v4, v4
	v_add_u32_e32 v5, s6, v1
	v_mul_f32_e32 v4, 0x4f7ffffe, v4
	v_cvt_u32_f32_e32 v4, v4
	v_mul_lo_u32 v1, v3, v4
	v_mul_hi_u32 v1, v4, v1
	v_add_u32_e32 v1, v4, v1
	v_mul_hi_u32 v1, v5, v1
	v_mul_lo_u32 v3, v1, v2
	v_sub_u32_e32 v3, v5, v3
	v_add_u32_e32 v4, 1, v1
	v_cmp_ge_u32_e32 vcc, v3, v2
	s_nop 1
	v_cndmask_b32_e32 v1, v1, v4, vcc
	v_sub_u32_e32 v4, v3, v2
	v_cndmask_b32_e32 v3, v3, v4, vcc
	v_add_u32_e32 v4, 1, v1
	v_cmp_ge_u32_e32 vcc, v3, v2
	v_add_u32_e32 v3, 1, v5
	s_nop 0
	v_cndmask_b32_e32 v1, v1, v4, vcc
	v_mul_lo_u32 v4, v2, v1
	v_add_u32_e32 v2, v4, v2
	v_cmp_ne_u32_e32 vcc, v3, v2
	s_and_saveexec_b64 s[6:7], vcc
	s_xor_b64 s[6:7], exec, s[6:7]
	s_cbranch_execz .LBB0_362
	s_waitcnt lgkmcnt(0)
	v_mov_b32_e32 v0, 0x2000
	s_getreg_b32 s10, hwreg(HW_REG_XCC_ID, 0, 4)
	s_lshl_b32 s10, s10, 8
	s_sub_u32 s10, s4, s10
	s_subb_u32 s11, s5, 0
	s_add_u32 s10, s10, 0x3500
	s_addc_u32 s11, s11, 0
	v_mov_b32_e32 v0, 0
	global_load_dword v0, v0, s[10:11] sc1
	s_waitcnt vmcnt(0)
	v_cmp_eq_u32_e32 vcc, v0, v1
	s_and_saveexec_b64 s[8:9], vcc
	s_cbranch_execz .LBB0_361
	s_mov_b32 s22, 1
	s_mov_b64 s[12:13], 0
	v_mov_b32_e32 v0, 0
	s_branch .LBB0_352

; __device__ __forceinline__ unsigned xb_ld(unsigned* p)              { return __hip_atomic_load(p, __ATOMIC_RELAXED, __HIP_MEMORY_SCOPE_AGENT); }
; __device__ __forceinline__ unsigned xb_add(unsigned* p, unsigned v) { return __hip_atomic_fetch_add(p, v, __ATOMIC_RELAXED, __HIP_MEMORY_SCOPE_AGENT); }
; #define XB_SPIN(cond, bar) do { unsigned _sp = 0; while (cond) { __builtin_amdgcn_s_sleep(1); \
;     if ((++_sp & 255u) == 0u) { if (xb_ld(&(bar)[XB_TMO])) break; if (_sp > XB_SPIN_CAP) { atomicAdd(&(bar)[XB_TMO], 1u); break; } } } } while (0)
; __device__ __forceinline__ void grid_barrier(unsigned* bar, unsigned G, int tid, volatile LAS unsigned* st) {
;     ...
;         const unsigned old = xb_add(&bar[XB_XSUB(x)], 1u);
;         const unsigned gen = old / nloc;
;         if (old + 1u == (gen + 1u) * nloc) {
;             __builtin_amdgcn_fence(__ATOMIC_RELEASE, "agent");
;             asm volatile("s_waitcnt vmcnt(0)" ::: "memory");
;             const unsigned og = xb_add(&bar[XB_TOP], 1u);
;             const unsigned tg = og / nx;
;             if (og + 1u == (tg + 1u) * nx) xb_add(&bar[XB_TOPGEN], 1u);
;             else XB_SPIN(xb_ld(&bar[XB_TOPGEN]) == tg, bar);
;             __builtin_amdgcn_fence(__ATOMIC_ACQUIRE, "agent");
;             xb_add(&bar[XB_XGEN(x)], 1u);
;             asm volatile("s_waitcnt vmcnt(0)" ::: "memory");
;         } else {
;             XB_SPIN(xb_ld(&bar[XB_XGEN(x)]) == gen, bar);
;             __builtin_amdgcn_fence(__ATOMIC_ACQUIRE, "agent");
;             asm volatile("s_waitcnt vmcnt(0)" ::: "memory");
;         }
.LBB0_875:
	s_or_b64 exec, exec, s[6:7]
	v_cvt_f32_u32_e32 v4, v2
	s_waitcnt vmcnt(0)
	v_readfirstlane_b32 s4, v3
	v_sub_u32_e32 v3, 0, v2
	v_rcp_iflag_f32_e32 v4, v4
	v_add_u32_e32 v5, s4, v1
	v_mul_f32_e32 v4, 0x4f7ffffe, v4
	v_cvt_u32_f32_e32 v4, v4
	v_mul_lo_u32 v1, v3, v4
	v_mul_hi_u32 v1, v4, v1
	v_add_u32_e32 v1, v4, v1
	v_mul_hi_u32 v1, v5, v1
	v_mul_lo_u32 v3, v1, v2
	v_sub_u32_e32 v3, v5, v3
	v_add_u32_e32 v4, 1, v1
	v_cmp_ge_u32_e32 vcc, v3, v2
	s_nop 1
	v_cndmask_b32_e32 v1, v1, v4, vcc
	v_sub_u32_e32 v4, v3, v2
	v_cndmask_b32_e32 v3, v3, v4, vcc
	v_add_u32_e32 v4, 1, v1
	v_cmp_ge_u32_e32 vcc, v3, v2
	v_add_u32_e32 v3, 1, v5
	s_nop 0
	v_cndmask_b32_e32 v1, v1, v4, vcc
	v_mul_lo_u32 v4, v2, v1
	v_add_u32_e32 v2, v4, v2
	v_cmp_ne_u32_e32 vcc, v3, v2
	s_and_saveexec_b64 s[4:5], vcc
	s_xor_b64 s[4:5], exec, s[4:5]
	s_cbranch_execz .LBB0_889
	s_waitcnt lgkmcnt(0)
	s_getreg_b32 s10, hwreg(HW_REG_XCC_ID, 0, 4)
	s_lshl_b32 s10, s10, 8
	s_sub_u32 s10, s2, s10
	s_subb_u32 s11, s3, 0
	s_add_u32 s10, s10, 0x3500
	s_addc_u32 s11, s11, 0
	v_mov_b32_e32 v0, 0
	global_load_dword v0, v0, s[10:11] sc1
	s_waitcnt vmcnt(0)
	v_cmp_eq_u32_e32 vcc, v0, v1
	s_and_saveexec_b64 s[6:7], vcc
	s_cbranch_execz .LBB0_888
	s_mov_b32 s23, 1
	s_mov_b64 s[12:13], 0
	s_branch .LBB0_879

; __device__ __forceinline__ unsigned xb_ld(unsigned* p)              { return __hip_atomic_load(p, __ATOMIC_RELAXED, __HIP_MEMORY_SCOPE_AGENT); }
; __device__ __forceinline__ unsigned xb_add(unsigned* p, unsigned v) { return __hip_atomic_fetch_add(p, v, __ATOMIC_RELAXED, __HIP_MEMORY_SCOPE_AGENT); }
; #define XB_SPIN(cond, bar) do { unsigned _sp = 0; while (cond) { __builtin_amdgcn_s_sleep(1); \
;     if ((++_sp & 255u) == 0u) { if (xb_ld(&(bar)[XB_TMO])) break; if (_sp > XB_SPIN_CAP) { atomicAdd(&(bar)[XB_TMO], 1u); break; } } } } while (0)
; __device__ __forceinline__ void grid_barrier(unsigned* bar, unsigned G, int tid, volatile LAS unsigned* st) {
;     ...
;         const unsigned old = xb_add(&bar[XB_XSUB(x)], 1u);
;         const unsigned gen = old / nloc;
;         if (old + 1u == (gen + 1u) * nloc) {
;             __builtin_amdgcn_fence(__ATOMIC_RELEASE, "agent");
;             asm volatile("s_waitcnt vmcnt(0)" ::: "memory");
;             const unsigned og = xb_add(&bar[XB_TOP], 1u);
;             const unsigned tg = og / nx;
;             if (og + 1u == (tg + 1u) * nx) xb_add(&bar[XB_TOPGEN], 1u);
;             else XB_SPIN(xb_ld(&bar[XB_TOPGEN]) == tg, bar);
;             __builtin_amdgcn_fence(__ATOMIC_ACQUIRE, "agent");
;             xb_add(&bar[XB_XGEN(x)], 1u);
;             asm volatile("s_waitcnt vmcnt(0)" ::: "memory");
;         } else {
;             XB_SPIN(xb_ld(&bar[XB_XGEN(x)]) == gen, bar);
;             __builtin_amdgcn_fence(__ATOMIC_ACQUIRE, "agent");
;             asm volatile("s_waitcnt vmcnt(0)" ::: "memory");
;         }
.LBB0_996:
	s_or_b64 exec, exec, s[6:7]
	v_cvt_f32_u32_e32 v4, v2
	s_waitcnt vmcnt(0)
	v_readfirstlane_b32 s4, v3
	v_sub_u32_e32 v3, 0, v2
	v_rcp_iflag_f32_e32 v4, v4
	v_add_u32_e32 v5, s4, v1
	v_mul_f32_e32 v4, 0x4f7ffffe, v4
	v_cvt_u32_f32_e32 v4, v4
	v_mul_lo_u32 v1, v3, v4
	v_mul_hi_u32 v1, v4, v1
	v_add_u32_e32 v1, v4, v1
	v_mul_hi_u32 v1, v5, v1
	v_mul_lo_u32 v3, v1, v2
	v_sub_u32_e32 v3, v5, v3
	v_add_u32_e32 v4, 1, v1
	v_cmp_ge_u32_e32 vcc, v3, v2
	s_nop 1
	v_cndmask_b32_e32 v1, v1, v4, vcc
	v_sub_u32_e32 v4, v3, v2
	v_cndmask_b32_e32 v3, v3, v4, vcc
	v_add_u32_e32 v4, 1, v1
	v_cmp_ge_u32_e32 vcc, v3, v2
	v_add_u32_e32 v3, 1, v5
	s_nop 0
	v_cndmask_b32_e32 v1, v1, v4, vcc
	v_mul_lo_u32 v4, v2, v1
	v_add_u32_e32 v2, v4, v2
	v_cmp_ne_u32_e32 vcc, v3, v2
	s_and_saveexec_b64 s[4:5], vcc
	s_xor_b64 s[4:5], exec, s[4:5]
	s_cbranch_execz .LBB0_1010
	s_waitcnt lgkmcnt(0)
	s_getreg_b32 s8, hwreg(HW_REG_XCC_ID, 0, 4)
	s_lshl_b32 s8, s8, 8
	s_sub_u32 s8, s2, s8
	s_subb_u32 s9, s3, 0
	s_add_u32 s8, s8, 0x3500
	s_addc_u32 s9, s9, 0
	v_mov_b32_e32 v0, 0
	global_load_dword v0, v0, s[8:9] sc1
	s_waitcnt vmcnt(0)
	v_cmp_eq_u32_e32 vcc, v0, v1
	s_and_saveexec_b64 s[6:7], vcc
	s_cbranch_execz .LBB0_1009
	s_mov_b32 s20, 1
	s_mov_b64 s[10:11], 0
	s_branch .LBB0_1000

; __device__ __forceinline__ unsigned xb_ld(unsigned* p)              { return __hip_atomic_load(p, __ATOMIC_RELAXED, __HIP_MEMORY_SCOPE_AGENT); }
; __device__ __forceinline__ unsigned xb_add(unsigned* p, unsigned v) { return __hip_atomic_fetch_add(p, v, __ATOMIC_RELAXED, __HIP_MEMORY_SCOPE_AGENT); }
; #define XB_SPIN(cond, bar) do { unsigned _sp = 0; while (cond) { __builtin_amdgcn_s_sleep(1); \
;     if ((++_sp & 255u) == 0u) { if (xb_ld(&(bar)[XB_TMO])) break; if (_sp > XB_SPIN_CAP) { atomicAdd(&(bar)[XB_TMO], 1u); break; } } } } while (0)
; __device__ __forceinline__ void grid_barrier(unsigned* bar, unsigned G, int tid, volatile LAS unsigned* st) {
;     ...
;         const unsigned old = xb_add(&bar[XB_XSUB(x)], 1u);
;         const unsigned gen = old / nloc;
;         if (old + 1u == (gen + 1u) * nloc) {
;             __builtin_amdgcn_fence(__ATOMIC_RELEASE, "agent");
;             asm volatile("s_waitcnt vmcnt(0)" ::: "memory");
;             const unsigned og = xb_add(&bar[XB_TOP], 1u);
;             const unsigned tg = og / nx;
;             if (og + 1u == (tg + 1u) * nx) xb_add(&bar[XB_TOPGEN], 1u);
;             else XB_SPIN(xb_ld(&bar[XB_TOPGEN]) == tg, bar);
;             __builtin_amdgcn_fence(__ATOMIC_ACQUIRE, "agent");
;             xb_add(&bar[XB_XGEN(x)], 1u);
;             asm volatile("s_waitcnt vmcnt(0)" ::: "memory");
;         } else {
;             XB_SPIN(xb_ld(&bar[XB_XGEN(x)]) == gen, bar);
;             __builtin_amdgcn_fence(__ATOMIC_ACQUIRE, "agent");
;             asm volatile("s_waitcnt vmcnt(0)" ::: "memory");
;         }
.LBB0_1371:
	s_or_b64 exec, exec, s[8:9]
	v_cvt_f32_u32_e32 v4, v2
	s_waitcnt vmcnt(0)
	v_readfirstlane_b32 s6, v3
	v_sub_u32_e32 v3, 0, v2
	v_rcp_iflag_f32_e32 v4, v4
	v_add_u32_e32 v5, s6, v1
	v_mul_f32_e32 v4, 0x4f7ffffe, v4
	v_cvt_u32_f32_e32 v4, v4
	v_mul_lo_u32 v1, v3, v4
	v_mul_hi_u32 v1, v4, v1
	v_add_u32_e32 v1, v4, v1
	v_mul_hi_u32 v1, v5, v1
	v_mul_lo_u32 v3, v1, v2
	v_sub_u32_e32 v3, v5, v3
	v_add_u32_e32 v4, 1, v1
	v_cmp_ge_u32_e32 vcc, v3, v2
	s_nop 1
	v_cndmask_b32_e32 v1, v1, v4, vcc
	v_sub_u32_e32 v4, v3, v2
	v_cndmask_b32_e32 v3, v3, v4, vcc
	v_add_u32_e32 v4, 1, v1
	v_cmp_ge_u32_e32 vcc, v3, v2
	v_add_u32_e32 v3, 1, v5
	s_nop 0
	v_cndmask_b32_e32 v1, v1, v4, vcc
	v_mul_lo_u32 v4, v2, v1
	v_add_u32_e32 v2, v4, v2
	v_cmp_ne_u32_e32 vcc, v3, v2
	s_and_saveexec_b64 s[6:7], vcc
	s_xor_b64 s[6:7], exec, s[6:7]
	s_cbranch_execz .LBB0_1385
	s_waitcnt lgkmcnt(0)
	s_getreg_b32 s10, hwreg(HW_REG_XCC_ID, 0, 4)
	s_lshl_b32 s10, s10, 8
	s_sub_u32 s10, s4, s10
	s_subb_u32 s11, s5, 0
	s_add_u32 s10, s10, 0x3500
	s_addc_u32 s11, s11, 0
	v_mov_b32_e32 v0, 0
	global_load_dword v0, v0, s[10:11] sc1
	s_waitcnt vmcnt(0)
	v_cmp_eq_u32_e32 vcc, v0, v1
	s_and_saveexec_b64 s[8:9], vcc
	s_cbranch_execz .LBB0_1384
	s_mov_b32 s23, 1
	s_mov_b64 s[12:13], 0
	s_branch .LBB0_1375

; __device__ __forceinline__ unsigned xb_ld(unsigned* p)              { return __hip_atomic_load(p, __ATOMIC_RELAXED, __HIP_MEMORY_SCOPE_AGENT); }
; __device__ __forceinline__ unsigned xb_add(unsigned* p, unsigned v) { return __hip_atomic_fetch_add(p, v, __ATOMIC_RELAXED, __HIP_MEMORY_SCOPE_AGENT); }
; #define XB_SPIN(cond, bar) do { unsigned _sp = 0; while (cond) { __builtin_amdgcn_s_sleep(1); \
;     if ((++_sp & 255u) == 0u) { if (xb_ld(&(bar)[XB_TMO])) break; if (_sp > XB_SPIN_CAP) { atomicAdd(&(bar)[XB_TMO], 1u); break; } } } } while (0)
; __device__ __forceinline__ void grid_barrier(unsigned* bar, unsigned G, int tid, volatile LAS unsigned* st) {
;     ...
;         const unsigned old = xb_add(&bar[XB_XSUB(x)], 1u);
;         const unsigned gen = old / nloc;
;         if (old + 1u == (gen + 1u) * nloc) {
;             __builtin_amdgcn_fence(__ATOMIC_RELEASE, "agent");
;             asm volatile("s_waitcnt vmcnt(0)" ::: "memory");
;             const unsigned og = xb_add(&bar[XB_TOP], 1u);
;             const unsigned tg = og / nx;
;             if (og + 1u == (tg + 1u) * nx) xb_add(&bar[XB_TOPGEN], 1u);
;             else XB_SPIN(xb_ld(&bar[XB_TOPGEN]) == tg, bar);
;             __builtin_amdgcn_fence(__ATOMIC_ACQUIRE, "agent");
;             xb_add(&bar[XB_XGEN(x)], 1u);
;             asm volatile("s_waitcnt vmcnt(0)" ::: "memory");
;         } else {
;             XB_SPIN(xb_ld(&bar[XB_XGEN(x)]) == gen, bar);
;             __builtin_amdgcn_fence(__ATOMIC_ACQUIRE, "agent");
;             asm volatile("s_waitcnt vmcnt(0)" ::: "memory");
;         }
.LBB0_1670:
	s_or_b64 exec, exec, s[8:9]
	v_cvt_f32_u32_e32 v4, v2
	s_waitcnt vmcnt(0)
	v_readfirstlane_b32 s4, v3
	v_sub_u32_e32 v3, 0, v2
	v_rcp_iflag_f32_e32 v4, v4
	v_add_u32_e32 v5, s4, v1
	v_mul_f32_e32 v4, 0x4f7ffffe, v4
	v_cvt_u32_f32_e32 v4, v4
	v_mul_lo_u32 v1, v3, v4
	v_mul_hi_u32 v1, v4, v1
	v_add_u32_e32 v1, v4, v1
	v_mul_hi_u32 v1, v5, v1
	v_mul_lo_u32 v3, v1, v2
	v_sub_u32_e32 v3, v5, v3
	v_add_u32_e32 v4, 1, v1
	v_cmp_ge_u32_e32 vcc, v3, v2
	s_nop 1
	v_cndmask_b32_e32 v1, v1, v4, vcc
	v_sub_u32_e32 v4, v3, v2
	v_cndmask_b32_e32 v3, v3, v4, vcc
	v_add_u32_e32 v4, 1, v1
	v_cmp_ge_u32_e32 vcc, v3, v2
	v_add_u32_e32 v3, 1, v5
	s_nop 0
	v_cndmask_b32_e32 v1, v1, v4, vcc
	v_mul_lo_u32 v4, v2, v1
	v_add_u32_e32 v2, v4, v2
	v_cmp_ne_u32_e32 vcc, v3, v2
	s_and_saveexec_b64 s[4:5], vcc
	s_xor_b64 s[4:5], exec, s[4:5]
	s_cbranch_execz .LBB0_1684
	s_waitcnt lgkmcnt(0)
	s_getreg_b32 s10, hwreg(HW_REG_XCC_ID, 0, 4)
	s_lshl_b32 s10, s10, 8
	s_sub_u32 s10, s2, s10
	s_subb_u32 s11, s3, 0
	s_add_u32 s10, s10, 0x3500
	s_addc_u32 s11, s11, 0
	v_mov_b32_e32 v0, 0
	global_load_dword v0, v0, s[10:11] sc1
	s_waitcnt vmcnt(0)
	v_cmp_eq_u32_e32 vcc, v0, v1
	s_and_saveexec_b64 s[8:9], vcc
	s_cbranch_execz .LBB0_1683
	s_mov_b32 s23, 1
	s_mov_b64 s[12:13], 0
	s_branch .LBB0_1674

; __device__ __forceinline__ unsigned xb_ld(unsigned* p)              { return __hip_atomic_load(p, __ATOMIC_RELAXED, __HIP_MEMORY_SCOPE_AGENT); }
; __device__ __forceinline__ unsigned xb_add(unsigned* p, unsigned v) { return __hip_atomic_fetch_add(p, v, __ATOMIC_RELAXED, __HIP_MEMORY_SCOPE_AGENT); }
; #define XB_SPIN(cond, bar) do { unsigned _sp = 0; while (cond) { __builtin_amdgcn_s_sleep(1); \
;     if ((++_sp & 255u) == 0u) { if (xb_ld(&(bar)[XB_TMO])) break; if (_sp > XB_SPIN_CAP) { atomicAdd(&(bar)[XB_TMO], 1u); break; } } } } while (0)
; __device__ __forceinline__ void grid_barrier(unsigned* bar, unsigned G, int tid, volatile LAS unsigned* st) {
;     ...
;         const unsigned old = xb_add(&bar[XB_XSUB(x)], 1u);
;         const unsigned gen = old / nloc;
;         if (old + 1u == (gen + 1u) * nloc) {
;             __builtin_amdgcn_fence(__ATOMIC_RELEASE, "agent");
;             asm volatile("s_waitcnt vmcnt(0)" ::: "memory");
;             const unsigned og = xb_add(&bar[XB_TOP], 1u);
;             const unsigned tg = og / nx;
;             if (og + 1u == (tg + 1u) * nx) xb_add(&bar[XB_TOPGEN], 1u);
;             else XB_SPIN(xb_ld(&bar[XB_TOPGEN]) == tg, bar);
;             __builtin_amdgcn_fence(__ATOMIC_ACQUIRE, "agent");
;             xb_add(&bar[XB_XGEN(x)], 1u);
;             asm volatile("s_waitcnt vmcnt(0)" ::: "memory");
;         } else {
;             XB_SPIN(xb_ld(&bar[XB_XGEN(x)]) == gen, bar);
;             __builtin_amdgcn_fence(__ATOMIC_ACQUIRE, "agent");
;             asm volatile("s_waitcnt vmcnt(0)" ::: "memory");
;         }
.LBB0_2049:
	s_or_b64 exec, exec, s[8:9]
	v_cvt_f32_u32_e32 v4, v2
	s_waitcnt vmcnt(0)
	v_readfirstlane_b32 s6, v3
	v_sub_u32_e32 v3, 0, v2
	v_rcp_iflag_f32_e32 v4, v4
	v_add_u32_e32 v5, s6, v1
	v_mul_f32_e32 v4, 0x4f7ffffe, v4
	v_cvt_u32_f32_e32 v4, v4
	v_mul_lo_u32 v1, v3, v4
	v_mul_hi_u32 v1, v4, v1
	v_add_u32_e32 v1, v4, v1
	v_mul_hi_u32 v1, v5, v1
	v_mul_lo_u32 v3, v1, v2
	v_sub_u32_e32 v3, v5, v3
	v_add_u32_e32 v4, 1, v1
	v_cmp_ge_u32_e32 vcc, v3, v2
	s_nop 1
	v_cndmask_b32_e32 v1, v1, v4, vcc
	v_sub_u32_e32 v4, v3, v2
	v_cndmask_b32_e32 v3, v3, v4, vcc
	v_add_u32_e32 v4, 1, v1
	v_cmp_ge_u32_e32 vcc, v3, v2
	v_add_u32_e32 v3, 1, v5
	s_nop 0
	v_cndmask_b32_e32 v1, v1, v4, vcc
	v_mul_lo_u32 v4, v2, v1
	v_add_u32_e32 v2, v4, v2
	v_cmp_ne_u32_e32 vcc, v3, v2
	s_and_saveexec_b64 s[6:7], vcc
	s_xor_b64 s[6:7], exec, s[6:7]
	s_cbranch_execz .LBB0_2063
	s_waitcnt lgkmcnt(0)
	s_getreg_b32 s10, hwreg(HW_REG_XCC_ID, 0, 4)
	s_lshl_b32 s10, s10, 8
	s_sub_u32 s10, s2, s10
	s_subb_u32 s11, s3, 0
	s_add_u32 s10, s10, 0x3500
	s_addc_u32 s11, s11, 0
	v_mov_b32_e32 v0, 0
	global_load_dword v0, v0, s[10:11] sc1
	s_waitcnt vmcnt(0)
	v_cmp_eq_u32_e32 vcc, v0, v1
	s_and_saveexec_b64 s[8:9], vcc
	s_cbranch_execz .LBB0_2062
	s_mov_b32 s23, 1
	s_mov_b64 s[12:13], 0
	s_branch .LBB0_2053
